# hyena latent: per channel iteration, two dummy loads per thread touch all 12 operand rows (96 KB) so the serialized conv3 tap loads hit in cache
# speedup vs baseline: 1.0293x; 1.0293x over previous
.LBB0_1341:
	s_or_b64 exec, exec, s[12:13]
	v_readlane_b32 s0, v253, 23
	v_readlane_b32 s1, v253, 24
	s_load_dwordx2 s[38:39], s[0:1], 0x78
	s_waitcnt lgkmcnt(0)
	s_load_dwordx2 s[40:41], s[0:1], 0x80
	s_waitcnt lgkmcnt(0)
	s_load_dwordx2 s[4:5], s[0:1], 0xa8
	s_waitcnt lgkmcnt(0)
	s_load_dwordx2 s[44:45], s[0:1], 0xb0
	s_waitcnt lgkmcnt(0)
	s_cmpk_lt_i32 s76, 0x200
	s_load_dwordx2 s[46:47], s[0:1], 0xb8
	s_waitcnt lgkmcnt(0)
	s_cselect_b64 s[0:1], -1, 0
	v_writelane_b32 v253, s0, 52
	s_cmpk_gt_i32 s76, 0x1ff
	s_cselect_b64 s[2:3], -1, 0
	v_writelane_b32 v253, s1, 53
	s_add_u32 s0, s84, 0x2da00000
	s_addc_u32 s1, s85, 0
	v_writelane_b32 v253, s0, 54
	s_movk_i32 s33, 0x200
	s_nop 0
	v_writelane_b32 v253, s1, 55
	v_writelane_b32 v253, s2, 56
	s_and_b64 vcc, exec, s[2:3]
	s_nop 0
	v_writelane_b32 v253, s3, 57
	v_writelane_b32 v253, s76, 58
	s_nop 1
	v_writelane_b32 v253, s77, 59
	s_cbranch_vccnz .LBB0_1817
	v_writelane_b32 v253, s4, 60
	v_and_b32_e32 v8, 31, v150
	v_lshlrev_b32_e32 v8, 3, v8
	v_writelane_b32 v253, s5, 61
	v_mov_b32_e32 v9, 0
	v_readlane_b32 s2, v253, 29
	v_readlane_b32 s3, v253, 30
	s_mov_b32 s0, 0xf000
	v_add_u32_e32 v42, 0x1000, v128
	v_lshl_add_u64 v[10:11], s[2:3], 0, v[8:9]
	v_and_b32_e32 v8, 1, v150
	v_add_co_u32_e32 v16, vcc, s0, v10
	v_lshlrev_b32_e32 v8, 3, v8
	v_add_u32_e32 v44, 0x1800, v128
	v_add_u32_e32 v46, 0x1c00, v128
	v_addc_co_u32_e32 v17, vcc, 0, v11, vcc
	v_lshl_add_u64 v[18:19], s[2:3], 0, v[8:9]
	v_ashrrev_i32_e32 v43, 31, v42
	v_ashrrev_i32_e32 v45, 31, v44
	v_ashrrev_i32_e32 v47, 31, v46
	v_add_co_u32_e32 v24, vcc, s0, v18
	v_lshl_add_u64 v[0:1], v[128:129], 3, s[2:3]
	v_lshl_add_u64 v[2:3], v[42:43], 3, s[2:3]
	v_lshl_add_u64 v[4:5], v[44:45], 3, s[2:3]
	v_lshl_add_u64 v[6:7], v[46:47], 3, s[2:3]
	v_addc_co_u32_e32 v25, vcc, 0, v19, vcc
	global_load_dwordx2 v[0:1], v[0:1], off
	s_nop 0
	global_load_dwordx2 v[2:3], v[2:3], off
	s_nop 0
	global_load_dwordx2 v[4:5], v[4:5], off
	s_nop 0
	global_load_dwordx2 v[6:7], v[6:7], off
	s_nop 0
	global_load_dwordx2 v[10:11], v[16:17], off
	global_load_dwordx2 v[12:13], v[16:17], off offset:2048
	global_load_dwordx2 v[14:15], v[16:17], off offset:3072
	s_nop 0
	global_load_dwordx2 v[16:17], v[16:17], off offset:3584
	s_nop 0
	global_load_dwordx2 v[18:19], v[24:25], off offset:3840
	global_load_dwordx2 v[20:21], v[24:25], off offset:3968
	global_load_dwordx2 v[22:23], v[24:25], off offset:4032
	s_nop 0
	global_load_dwordx2 v[24:25], v[24:25], off offset:4064
	v_ashrrev_i32_e32 v8, 4, v128
	v_lshlrev_b32_e32 v8, 3, v8
	v_and_b32_e32 v8, -16, v8
	v_lshlrev_b32_e32 v106, 3, v128
	v_add3_u32 v107, 0, v8, v106
	v_ashrrev_i32_e32 v8, 4, v42
	v_lshlrev_b32_e32 v8, 3, v8
	v_add_u32_e32 v28, 0x200, v128
	v_and_b32_e32 v8, -16, v8
	v_add3_u32 v108, 0, v8, v106
	v_ashrrev_i32_e32 v8, 4, v28
	v_lshlrev_b32_e32 v8, 3, v8
	v_and_b32_e32 v8, -16, v8
	v_add3_u32 v109, 0, v8, v106
	v_add_u32_e32 v8, 0x1200, v128
	v_ashrrev_i32_e32 v8, 4, v8
	v_lshlrev_b32_e32 v8, 3, v8
	v_add_u32_e32 v30, 0x400, v128
	v_and_b32_e32 v8, -16, v8
	v_add3_u32 v110, 0, v8, v106
	v_ashrrev_i32_e32 v8, 4, v30
	v_lshlrev_b32_e32 v8, 3, v8
	v_and_b32_e32 v8, -16, v8
	v_add3_u32 v111, 0, v8, v106
	v_add_u32_e32 v8, 0x1400, v128
	v_ashrrev_i32_e32 v8, 4, v8
	v_lshlrev_b32_e32 v8, 3, v8
	v_add_u32_e32 v32, 0x600, v128
	v_and_b32_e32 v8, -16, v8
	v_add3_u32 v112, 0, v8, v106
	v_ashrrev_i32_e32 v8, 4, v32
	v_lshlrev_b32_e32 v8, 3, v8
	v_and_b32_e32 v8, -16, v8
	v_add3_u32 v113, 0, v8, v106
	v_add_u32_e32 v8, 0x1600, v128
	v_ashrrev_i32_e32 v8, 4, v8
	v_lshlrev_b32_e32 v8, 3, v8
	v_add_u32_e32 v34, 0x800, v128
	v_and_b32_e32 v8, -16, v8
	v_add3_u32 v114, 0, v8, v106
	v_ashrrev_i32_e32 v8, 4, v34
	v_lshlrev_b32_e32 v8, 3, v8
	v_and_b32_e32 v8, -16, v8
	v_add3_u32 v115, 0, v8, v106
	v_ashrrev_i32_e32 v8, 4, v44
	v_lshlrev_b32_e32 v8, 3, v8
	s_movk_i32 s0, 0xfff
	v_add_u32_e32 v36, 0xa00, v128
	v_and_b32_e32 v8, -16, v8
	v_cmp_gt_i32_e64 s[6:7], s0, v128
	s_movk_i32 s0, 0xfe00
	v_add3_u32 v116, 0, v8, v106
	v_ashrrev_i32_e32 v8, 4, v36
	v_cmp_lt_i32_e64 s[8:9], s0, v128
	s_movk_i32 s0, 0xdff
	v_lshlrev_b32_e32 v8, 3, v8
	v_cmp_gt_i32_e64 s[10:11], s0, v128
	s_movk_i32 s0, 0xfc00
	v_and_b32_e32 v8, -16, v8
	v_cmp_lt_i32_e64 s[12:13], s0, v128
	s_movk_i32 s0, 0xbff
	v_add3_u32 v117, 0, v8, v106
	v_add_u32_e32 v8, 0x1a00, v128
	v_cmp_gt_i32_e64 s[14:15], s0, v128
	s_movk_i32 s0, 0xfa00
	v_ashrrev_i32_e32 v8, 4, v8
	v_cmp_lt_i32_e64 s[16:17], s0, v128
	s_movk_i32 s0, 0x9ff
	v_lshlrev_b32_e32 v8, 3, v8
	v_cmp_gt_i32_e64 s[18:19], s0, v128
	s_movk_i32 s0, 0xf800
	v_add_u32_e32 v38, 0xc00, v128
	v_and_b32_e32 v8, -16, v8
	v_cmp_lt_i32_e64 s[20:21], s0, v128
	s_movk_i32 s0, 0x7ff
	v_add3_u32 v118, 0, v8, v106
	v_ashrrev_i32_e32 v8, 4, v38
	v_cmp_gt_i32_e64 s[22:23], s0, v128
	s_movk_i32 s0, 0xf600
	v_lshlrev_b32_e32 v8, 3, v8
	v_cmp_lt_i32_e64 s[24:25], s0, v128
	s_movk_i32 s0, 0x5ff
	v_and_b32_e32 v8, -16, v8
	v_cmp_gt_i32_e64 s[26:27], s0, v128
	s_movk_i32 s0, 0xf400
	v_add3_u32 v119, 0, v8, v106
	v_ashrrev_i32_e32 v8, 4, v46
	v_cmp_lt_i32_e64 s[28:29], s0, v128
	s_movk_i32 s0, 0x3ff
	v_lshlrev_b32_e32 v8, 3, v8
	v_cmp_gt_i32_e64 s[30:31], s0, v128
	v_add_u32_e32 v40, 0xe00, v128
	s_movk_i32 s0, 0xf200
	v_and_b32_e32 v8, -16, v8
	v_cmp_lt_i32_e64 s[34:35], s0, v128
	s_movk_i32 s0, 0x1ff
	v_add3_u32 v120, 0, v8, v106
	v_ashrrev_i32_e32 v8, 4, v40
	v_cmp_gt_i32_e64 s[36:37], s0, v128
	v_lshlrev_b32_e32 v8, 3, v8
	v_readlane_b32 s0, v253, 54
	v_and_b32_e32 v8, -16, v8
	v_readlane_b32 s1, v253, 55
	v_add3_u32 v121, 0, v8, v106
	v_add_u32_e32 v8, 0x1e00, v128
	v_lshl_add_u64 v[42:43], v[128:129], 1, s[0:1]
	v_readlane_b32 s0, v253, 0
	v_ashrrev_i32_e32 v8, 4, v8
	s_lshl_b32 s0, s0, 3
	s_mov_b32 s62, 0
	v_lshlrev_b32_e32 v8, 3, v8
	s_and_b32 s0, s0, 0xfffffe00
	s_mov_b32 s58, 0xbec3ef15
	v_and_b32_e32 v8, -16, v8
	v_lshl_add_u32 v123, v150, 3, s0
	v_lshl_add_u64 v[44:45], v[128:129], 2, s[84:85]
	s_mov_b64 s[2:3], 0x23000800
	s_mov_b32 s59, 0xbf6c835e
	s_mov_b32 s63, s62
	s_movk_i32 s57, 0x1000
	v_cmp_lt_i32_e64 s[4:5], 0, v128
	v_mov_b32_e32 v26, v128
	v_mov_b32_e32 v27, v9
	v_mov_b32_e32 v29, v9
	v_mov_b32_e32 v31, v9
	v_mov_b32_e32 v33, v9
	v_mov_b32_e32 v35, v9
	v_mov_b32_e32 v37, v9
	v_mov_b32_e32 v39, v9
	v_mov_b32_e32 v41, v9
	v_add3_u32 v122, 0, v8, v106
	v_sub_u32_e32 v124, 0, v123
	v_sub_u32_e32 v125, 0, v128
	v_lshl_add_u64 v[44:45], v[44:45], 0, s[2:3]
	v_mov_b32_e32 v126, 0x3000
	v_mov_b32_e32 v127, 0x2000
	v_mov_b32_e32 v130, 0x4000
	s_mov_b64 s[48:49], 0x1000
	s_mov_b64 s[50:51], 0x1400
	s_mov_b64 s[52:53], 0x1800
	s_mov_b64 s[54:55], 0x1c00
	s_mov_b32 s92, 0x11000
	s_mov_b32 s93, 0x21000
	s_add_i32 s2, 0, 0x19800
	s_mov_b32 s3, 0x12000
	s_mov_b32 s96, 0x20000
	s_mov_b32 s56, 0xbf3504f3
	s_mov_b32 s97, 0x3f3504f3
	s_mov_b32 s42, 0x3f6c835e
	s_mov_b32 s43, 0x3ec3ef15
	s_mov_b32 s60, s59
	s_mov_b32 s61, s58
	v_mov_b64_e32 v[184:185], s[62:63]
	s_mov_b32 s62, 0x39000000
	v_mov_b32_e32 v186, v9
	v_mov_b32_e32 v187, v9
	s_mov_b32 s63, s76
	v_readlane_b32 s98, v253, 3
	v_mbcnt_lo_u32_b32 v254, -1, 0
	v_mbcnt_hi_u32_b32 v254, -1, v254
	v_lshlrev_b32_e32 v254, 7, v254
	s_lshr_b32 s98, s98, 6
	s_and_b32 s99, s98, 3
	s_mul_i32 s99, s99, 0xc00000
	s_lshr_b32 s100, s98, 2
	s_lshl_b32 s100, s100, 22
	s_add_u32 s99, s99, s100
	s_add_u32 s99, s99, 0xed00000
	v_add_u32_e32 v254, s99, v254
	s_mov_b32 s100, 0
	s_cmp_lt_u32 s98, 4
	s_cselect_b32 s100, 0x800000, s100
	s_add_u32 s100, s84, s100
	s_addc_u32 s101, s85, 0
.LBB0_1343:
	s_mov_b32 s64, s63
	s_lshl_b32 s99, s64, 13
	v_add_u32_e32 v254, s99, v254
	global_load_dword v255, v254, s[84:85]
	global_load_dword v255, v254, s[100:101]
	v_subrev_u32_e32 v254, s99, v254
	s_ashr_i32 s65, s64, 31
	s_lshl_b64 s[70:71], s[64:65], 2
	s_add_u32 s72, s38, s70
	s_addc_u32 s73, s39, s71
	s_add_i32 s66, s64, 0x600
	s_ashr_i32 s67, s66, 31
	s_lshl_b64 s[68:69], s[66:67], 2
	s_add_u32 s68, s38, s68
	s_addc_u32 s69, s39, s69
	global_load_dword v153, v9, s[72:73]
	global_load_dword v154, v9, s[68:69]
	global_load_dword v152, v126, s[72:73]
	s_add_u32 s68, s40, s70
	s_addc_u32 s69, s41, s71
	global_load_dword v47, v9, s[68:69]
	global_load_dword v149, v9, s[72:73] offset:2048
	global_load_dword v151, v127, s[72:73]
	global_load_dword v148, v126, s[72:73] offset:2048
	global_load_dword v86, v9, s[68:69] offset:2048
	s_add_i32 s68, s64, 0x400
	s_ashr_i32 s69, s68, 31
	s_lshl_b64 s[74:75], s[68:69], 2
	s_add_u32 s76, s38, s74
	s_addc_u32 s77, s39, s75
	global_load_dword v133, v9, s[76:77]
	global_load_dword v135, v127, s[72:73] offset:2048
	global_load_dword v134, v130, s[72:73]
	s_add_u32 s72, s40, s74
	s_addc_u32 s73, s41, s75
	s_add_u32 s70, s46, s70
	global_load_dword v131, v9, s[72:73]
	s_addc_u32 s71, s47, s71
	s_lshl_b64 s[72:73], s[64:65], 13
	s_add_u32 s78, s90, s72
	s_addc_u32 s79, s91, s73
	v_lshl_add_u64 v[50:51], v[128:129], 1, s[78:79]
	global_load_dword v87, v9, s[70:71]
	global_load_dword v132, v9, s[70:71] offset:2048
	global_load_ushort v8, v[50:51], off
	s_waitcnt vmcnt(0)
	v_lshlrev_b32_e32 v8, 16, v8
	v_fma_f32 v48, v154, v8, v47
	s_and_saveexec_b64 s[70:71], s[4:5]
	s_cbranch_execz .LBB0_1345
	v_lshl_add_u64 v[52:53], v[26:27], 1, s[78:79]
	global_load_ushort v8, v[52:53], off offset:-2
	s_waitcnt vmcnt(0)
	v_lshlrev_b32_e32 v8, 16, v8
	v_fmac_f32_e32 v48, v153, v8

.LBB0_4120:
	s_or_b64 exec, exec, s[0:1]
	v_readlane_b32 s6, v253, 23
	v_readlane_b32 s7, v253, 24
	s_load_dwordx2 s[0:1], s[6:7], 0x78
	s_waitcnt lgkmcnt(0)
	s_load_dwordx2 s[4:5], s[6:7], 0x80
	s_waitcnt lgkmcnt(0)
	s_load_dwordx2 s[2:3], s[6:7], 0xa8
	s_waitcnt lgkmcnt(0)
	s_nop 0
	s_load_dwordx2 s[2:3], s[6:7], 0xb0
	s_waitcnt lgkmcnt(0)
	s_load_dwordx2 s[6:7], s[6:7], 0xb8
	s_waitcnt lgkmcnt(0)
	s_nop 0
	v_readlane_b32 s2, v253, 52
	v_readlane_b32 s3, v253, 53
	s_andn2_b64 vcc, exec, s[2:3]
	s_nop 0
	v_cndmask_b32_e64 v0, 0, 1, s[2:3]
	v_cmp_ne_u32_e64 s[8:9], 1, v0
	s_nop 1
	v_writelane_b32 v252, s8, 44
	s_nop 1
	v_writelane_b32 v252, s9, 45
	s_cbranch_vccnz .LBB0_4535
	s_add_u32 s47, s0, 0x4800
	s_addc_u32 s53, s1, 0
	s_add_u32 s2, s4, 0x1800
	s_addc_u32 s83, s5, 0
	v_writelane_b32 v253, s2, 44
	s_add_u32 s2, s6, 0x1000
	v_writelane_b32 v253, s2, 17
	s_addc_u32 s2, s7, 0
	v_writelane_b32 v253, s2, 13
	v_and_b32_e32 v8, 31, v150
	v_readlane_b32 s8, v253, 29
	v_readlane_b32 s9, v253, 30
	v_lshlrev_b32_e32 v8, 3, v8
	v_mov_b32_e32 v9, 0
	v_lshl_add_u64 v[10:11], s[8:9], 0, v[8:9]
	s_mov_b32 s2, 0xf000
	v_and_b32_e32 v8, 1, v150
	v_add_co_u32_e32 v16, vcc, s2, v10
	v_lshlrev_b32_e32 v8, 3, v8
	v_add_u32_e32 v40, 0x1000, v128
	v_add_u32_e32 v42, 0x1800, v128
	v_add_u32_e32 v44, 0x1c00, v128
	v_addc_co_u32_e32 v17, vcc, 0, v11, vcc
	v_lshl_add_u64 v[18:19], s[8:9], 0, v[8:9]
	v_ashrrev_i32_e32 v41, 31, v40
	v_ashrrev_i32_e32 v43, 31, v42
	v_ashrrev_i32_e32 v45, 31, v44
	v_add_co_u32_e32 v24, vcc, s2, v18
	v_lshl_add_u64 v[0:1], v[128:129], 3, s[8:9]
	v_lshl_add_u64 v[2:3], v[40:41], 3, s[8:9]
	v_lshl_add_u64 v[4:5], v[42:43], 3, s[8:9]
	v_lshl_add_u64 v[6:7], v[44:45], 3, s[8:9]
	v_addc_co_u32_e32 v25, vcc, 0, v19, vcc
	global_load_dwordx2 v[0:1], v[0:1], off
	s_nop 0
	global_load_dwordx2 v[2:3], v[2:3], off
	s_nop 0
	global_load_dwordx2 v[4:5], v[4:5], off
	s_nop 0
	global_load_dwordx2 v[6:7], v[6:7], off
	s_nop 0
	global_load_dwordx2 v[10:11], v[16:17], off
	global_load_dwordx2 v[12:13], v[16:17], off offset:2048
	global_load_dwordx2 v[14:15], v[16:17], off offset:3072
	s_nop 0
	global_load_dwordx2 v[16:17], v[16:17], off offset:3584
	s_nop 0
	global_load_dwordx2 v[18:19], v[24:25], off offset:3840
	global_load_dwordx2 v[20:21], v[24:25], off offset:3968
	global_load_dwordx2 v[22:23], v[24:25], off offset:4032
	s_nop 0
	global_load_dwordx2 v[24:25], v[24:25], off offset:4064
	v_ashrrev_i32_e32 v8, 4, v128
	v_lshlrev_b32_e32 v8, 3, v8
	v_and_b32_e32 v8, -16, v8
	v_lshlrev_b32_e32 v41, 3, v128
	v_add3_u32 v104, 0, v8, v41
	v_ashrrev_i32_e32 v8, 4, v40
	v_lshlrev_b32_e32 v8, 3, v8
	v_add_u32_e32 v26, 0x200, v128
	v_and_b32_e32 v8, -16, v8
	v_add3_u32 v105, 0, v8, v41
	v_ashrrev_i32_e32 v8, 4, v26
	v_lshlrev_b32_e32 v8, 3, v8
	v_and_b32_e32 v8, -16, v8
	v_add3_u32 v106, 0, v8, v41
	v_add_u32_e32 v8, 0x1200, v128
	v_ashrrev_i32_e32 v8, 4, v8
	v_lshlrev_b32_e32 v8, 3, v8
	v_add_u32_e32 v28, 0x400, v128
	v_and_b32_e32 v8, -16, v8
	v_add3_u32 v107, 0, v8, v41
	v_ashrrev_i32_e32 v8, 4, v28
	v_lshlrev_b32_e32 v8, 3, v8
	v_and_b32_e32 v8, -16, v8
	v_add3_u32 v108, 0, v8, v41
	v_add_u32_e32 v8, 0x1400, v128
	v_ashrrev_i32_e32 v8, 4, v8
	v_lshlrev_b32_e32 v8, 3, v8
	v_add_u32_e32 v30, 0x600, v128
	v_and_b32_e32 v8, -16, v8
	v_add3_u32 v109, 0, v8, v41
	v_ashrrev_i32_e32 v8, 4, v30
	v_lshlrev_b32_e32 v8, 3, v8
	v_and_b32_e32 v8, -16, v8
	v_add3_u32 v110, 0, v8, v41
	v_add_u32_e32 v8, 0x1600, v128
	v_ashrrev_i32_e32 v8, 4, v8
	v_lshlrev_b32_e32 v8, 3, v8
	v_add_u32_e32 v32, 0x800, v128
	v_and_b32_e32 v8, -16, v8
	v_add3_u32 v111, 0, v8, v41
	v_ashrrev_i32_e32 v8, 4, v32
	v_lshlrev_b32_e32 v8, 3, v8
	v_and_b32_e32 v8, -16, v8
	v_add3_u32 v112, 0, v8, v41
	v_ashrrev_i32_e32 v8, 4, v42
	v_lshlrev_b32_e32 v8, 3, v8
	v_add_u32_e32 v34, 0xa00, v128
	v_and_b32_e32 v8, -16, v8
	v_add3_u32 v113, 0, v8, v41
	v_ashrrev_i32_e32 v8, 4, v34
	v_lshlrev_b32_e32 v8, 3, v8
	v_and_b32_e32 v8, -16, v8
	s_movk_i32 s2, 0xfff
	v_add3_u32 v114, 0, v8, v41
	v_add_u32_e32 v8, 0x1a00, v128
	v_cmp_gt_i32_e64 s[10:11], s2, v128
	s_movk_i32 s2, 0xfe00
	v_ashrrev_i32_e32 v8, 4, v8
	v_cmp_lt_i32_e64 s[12:13], s2, v128
	s_movk_i32 s2, 0xdff
	v_lshlrev_b32_e32 v8, 3, v8
	v_cmp_gt_i32_e64 s[14:15], s2, v128
	s_movk_i32 s2, 0xfc00
	v_add_u32_e32 v36, 0xc00, v128
	v_and_b32_e32 v8, -16, v8
	v_cmp_lt_i32_e64 s[16:17], s2, v128
	s_movk_i32 s2, 0xbff
	v_add3_u32 v115, 0, v8, v41
	v_ashrrev_i32_e32 v8, 4, v36
	v_cmp_gt_i32_e64 s[18:19], s2, v128
	s_movk_i32 s2, 0xfa00
	v_lshlrev_b32_e32 v8, 3, v8
	v_cmp_lt_i32_e64 s[20:21], s2, v128
	s_movk_i32 s2, 0x9ff
	v_and_b32_e32 v8, -16, v8
	v_cmp_gt_i32_e64 s[22:23], s2, v128
	s_movk_i32 s2, 0xf800
	v_add3_u32 v116, 0, v8, v41
	v_ashrrev_i32_e32 v8, 4, v44
	v_cmp_lt_i32_e64 s[24:25], s2, v128
	s_movk_i32 s2, 0x7ff
	v_lshlrev_b32_e32 v8, 3, v8
	v_cmp_gt_i32_e64 s[26:27], s2, v128
	s_movk_i32 s2, 0xf600
	v_add_u32_e32 v38, 0xe00, v128
	v_and_b32_e32 v8, -16, v8
	v_cmp_lt_i32_e64 s[28:29], s2, v128
	s_movk_i32 s2, 0x5ff
	v_add3_u32 v117, 0, v8, v41
	v_ashrrev_i32_e32 v8, 4, v38
	v_cmp_gt_i32_e64 s[30:31], s2, v128
	s_movk_i32 s2, 0xf400
	v_lshlrev_b32_e32 v8, 3, v8
	v_cmp_lt_i32_e64 s[34:35], s2, v128
	s_movk_i32 s2, 0x3ff
	v_and_b32_e32 v8, -16, v8
	v_cmp_gt_i32_e64 s[36:37], s2, v128
	s_movk_i32 s2, 0xf200
	v_add3_u32 v118, 0, v8, v41
	v_add_u32_e32 v8, 0x1e00, v128
	v_cmp_lt_i32_e64 s[38:39], s2, v128
	s_movk_i32 s2, 0x1ff
	v_ashrrev_i32_e32 v8, 4, v8
	v_cmp_gt_i32_e64 s[40:41], s2, v128
	v_lshlrev_b32_e32 v8, 3, v8
	v_readlane_b32 s2, v253, 54
	v_and_b32_e32 v8, -16, v8
	v_readlane_b32 s3, v253, 55
	v_add3_u32 v119, 0, v8, v41
	s_mov_b32 s6, 0
	v_lshl_add_u64 v[40:41], v[128:129], 1, s[2:3]
	v_readlane_b32 s2, v253, 0
	s_lshl_b32 s2, s2, 3
	s_and_b32 s2, s2, 0xfffffe00
	s_mov_b32 s48, 0xbec3ef15
	s_mov_b32 s7, s6
	v_lshl_add_u32 v120, v150, 3, s2
	v_lshl_add_u64 v[42:43], v[128:129], 2, s[84:85]
	s_mov_b64 s[2:3], 0x23000800
	s_mov_b32 s49, 0xbf6c835e
	v_mov_b64_e32 v[180:181], s[6:7]
	v_readlane_b32 s6, v253, 58
	s_mov_b64 s[0:1], 0x1800
	s_mov_b64 s[4:5], 0x1000
	v_cmp_lt_i32_e64 s[8:9], 0, v128
	s_movk_i32 s33, 0x200
	v_mov_b32_e32 v27, v9
	v_mov_b32_e32 v29, v9
	v_mov_b32_e32 v31, v9
	v_mov_b32_e32 v33, v9
	v_mov_b32_e32 v35, v9
	v_mov_b32_e32 v37, v9
	v_mov_b32_e32 v39, v9
	v_sub_u32_e32 v121, 0, v120
	v_sub_u32_e32 v122, 0, v128
	v_lshl_add_u64 v[42:43], v[42:43], 0, s[2:3]
	v_mov_b32_e32 v123, 0x3000
	v_mov_b32_e32 v124, 0x2000
	v_mov_b32_e32 v125, 0x4000
	s_mov_b64 s[42:43], 0x1400
	s_mov_b64 s[44:45], 0x1c00
	s_mov_b32 s88, 0x11000
	s_mov_b32 s89, 0x21000
	s_add_i32 s96, 0, 0x19800
	s_mov_b32 s97, 0x12000
	s_mov_b32 s92, 0x20000
	s_mov_b32 s46, 0xbf3504f3
	s_mov_b32 s93, 0x3f3504f3
	s_mov_b32 s2, 0x3f6c835e
	s_mov_b32 s3, 0x3ec3ef15
	s_mov_b32 s50, s49
	s_mov_b32 s51, s48
	s_mov_b32 s52, 0x39000000
	v_mov_b32_e32 v182, v9
	v_mov_b32_e32 v183, v9
	s_mov_b32 s82, s6
	v_readlane_b32 s7, v253, 59
	v_readlane_b32 s98, v253, 3
	v_mbcnt_lo_u32_b32 v254, -1, 0
	v_mbcnt_hi_u32_b32 v254, -1, v254
	v_lshlrev_b32_e32 v254, 7, v254
	s_lshr_b32 s98, s98, 6
	s_and_b32 s99, s98, 3
	s_mul_i32 s99, s99, 0xc00000
	s_lshr_b32 s100, s98, 2
	s_lshl_b32 s100, s100, 22
	s_add_u32 s99, s99, s100
	s_add_u32 s99, s99, 0xed00000
	v_add_u32_e32 v254, s99, v254
	s_mov_b32 s100, 0
	s_cmp_lt_u32 s98, 4
	s_cselect_b32 s100, 0x800000, s100
	s_add_u32 s100, s84, s100
	s_addc_u32 s101, s85, 0
.LBB0_4122:
	s_mov_b32 s54, s82
	s_lshl_b32 s99, s54, 13
	v_add_u32_e32 v254, s99, v254
	global_load_dword v255, v254, s[84:85]
	global_load_dword v255, v254, s[100:101]
	v_subrev_u32_e32 v254, s99, v254
	s_ashr_i32 s55, s54, 31
	s_lshl_b64 s[6:7], s[54:55], 2
	s_add_u32 s66, s47, s6
	s_addc_u32 s67, s53, s7
	s_add_i32 s56, s54, 0x600
	s_ashr_i32 s57, s56, 31
	s_lshl_b64 s[58:59], s[56:57], 2
	s_add_u32 s58, s47, s58
	s_addc_u32 s59, s53, s59
	v_readlane_b32 s76, v253, 44
	global_load_dword v149, v9, s[66:67]
	global_load_dword v150, v9, s[58:59]
	global_load_dword v148, v123, s[66:67]
	s_add_u32 s58, s76, s6
	s_addc_u32 s59, s83, s7
	s_add_i32 s72, s54, 0x200
	s_ashr_i32 s73, s72, 31
	s_lshl_b64 s[68:69], s[72:73], 2
	global_load_dword v45, v9, s[58:59]
	s_add_u32 s58, s47, s68
	s_addc_u32 s59, s53, s69
	global_load_dword v146, v9, s[58:59]
	global_load_dword v147, v124, s[66:67]
	global_load_dword v145, v123, s[66:67] offset:2048
	s_add_u32 s58, s76, s68
	s_addc_u32 s59, s83, s69
	global_load_dword v84, v9, s[58:59]
	s_add_i32 s58, s54, 0x400
	s_ashr_i32 s59, s58, 31
	s_lshl_b64 s[70:71], s[58:59], 2
	s_add_u32 s74, s47, s70
	s_addc_u32 s75, s53, s71
	global_load_dword v130, v9, s[74:75]
	global_load_dword v132, v124, s[66:67] offset:2048
	global_load_dword v131, v125, s[66:67]
	s_add_u32 s66, s76, s70
	s_addc_u32 s67, s83, s71
	global_load_dword v126, v9, s[66:67]
	v_readlane_b32 s66, v253, 17
	s_add_u32 s6, s66, s6
	v_readlane_b32 s67, v253, 13
	s_addc_u32 s7, s67, s7
	global_load_dword v85, v9, s[6:7]
	s_add_u32 s6, s66, s68
	s_addc_u32 s7, s67, s69
	s_lshl_b64 s[68:69], s[54:55], 13
	global_load_dword v127, v9, s[6:7]
	s_add_u32 s6, s90, s68
	s_addc_u32 s7, s91, s69
	v_lshl_add_u64 v[48:49], v[128:129], 1, s[6:7]
	global_load_ushort v8, v[48:49], off
	s_waitcnt vmcnt(0)
	v_lshlrev_b32_e32 v8, 16, v8
	v_fma_f32 v46, v150, v8, v45
	s_and_saveexec_b64 s[66:67], s[8:9]
	s_cbranch_execz .LBB0_4124
	global_load_ushort v8, v[48:49], off offset:-2
	s_waitcnt vmcnt(0)
	v_lshlrev_b32_e32 v8, 16, v8
	v_fmac_f32_e32 v46, v149, v8

	.amdhsa_kernel _Z10fwd_kernel4Args
		.amdhsa_group_segment_fixed_size 0
		.amdhsa_private_segment_fixed_size 0
		.amdhsa_kernarg_size 528
		.amdhsa_user_sgpr_count 2
		.amdhsa_user_sgpr_dispatch_ptr 0
		.amdhsa_user_sgpr_queue_ptr 0
		.amdhsa_user_sgpr_kernarg_segment_ptr 1
		.amdhsa_user_sgpr_dispatch_id 0
		.amdhsa_user_sgpr_kernarg_preload_length 0
		.amdhsa_user_sgpr_kernarg_preload_offset 0
		.amdhsa_user_sgpr_private_segment_size 0
		.amdhsa_uses_dynamic_stack 0
		.amdhsa_enable_private_segment 0
		.amdhsa_system_sgpr_workgroup_id_x 1
		.amdhsa_system_sgpr_workgroup_id_y 0
		.amdhsa_system_sgpr_workgroup_id_z 0
		.amdhsa_system_sgpr_workgroup_info 0
		.amdhsa_system_vgpr_workitem_id 2
		.amdhsa_next_free_vgpr 256
		.amdhsa_next_free_sgpr 102
		.amdhsa_accum_offset 256
		.amdhsa_reserve_vcc 1
		.amdhsa_float_round_mode_32 0
		.amdhsa_float_round_mode_16_64 0
		.amdhsa_float_denorm_mode_32 3
		.amdhsa_float_denorm_mode_16_64 3
		.amdhsa_dx10_clamp 1
		.amdhsa_ieee_mode 1
		.amdhsa_fp16_overflow 0
		.amdhsa_tg_split 0
		.amdhsa_exception_fp_ieee_invalid_op 0
		.amdhsa_exception_fp_denorm_src 0
		.amdhsa_exception_fp_ieee_div_zero 0
		.amdhsa_exception_fp_ieee_overflow 0
		.amdhsa_exception_fp_ieee_underflow 0
		.amdhsa_exception_fp_ieee_inexact 0
		.amdhsa_exception_int_div_zero 0
	.end_amdhsa_kernel

amdhsa.kernels:
  - .agpr_count:     0
    .args:
      - .offset:         0
        .size:           272
        .value_kind:     by_value
      - .offset:         272
        .size:           4
        .value_kind:     hidden_block_count_x
      - .offset:         276
        .size:           4
        .value_kind:     hidden_block_count_y
      - .offset:         280
        .size:           4
        .value_kind:     hidden_block_count_z
      - .offset:         284
        .size:           2
        .value_kind:     hidden_group_size_x
      - .offset:         286
        .size:           2
        .value_kind:     hidden_group_size_y
      - .offset:         288
        .size:           2
        .value_kind:     hidden_group_size_z
      - .offset:         290
        .size:           2
        .value_kind:     hidden_remainder_x
      - .offset:         292
        .size:           2
        .value_kind:     hidden_remainder_y
      - .offset:         294
        .size:           2
        .value_kind:     hidden_remainder_z
      - .offset:         312
        .size:           8
        .value_kind:     hidden_global_offset_x
      - .offset:         320
        .size:           8
        .value_kind:     hidden_global_offset_y
      - .offset:         328
        .size:           8
        .value_kind:     hidden_global_offset_z
      - .offset:         336
        .size:           2
        .value_kind:     hidden_grid_dims
      - .offset:         360
        .size:           8
        .value_kind:     hidden_multigrid_sync_arg
      - .offset:         392
        .size:           4
        .value_kind:     hidden_dynamic_lds_size
    .group_segment_fixed_size: 0
    .kernarg_segment_align: 8
    .kernarg_segment_size: 528
    .language:       OpenCL C
    .language_version:
      - 2
      - 0
    .max_flat_workgroup_size: 512
    .name:           _Z10fwd_kernel4Args
    .private_segment_fixed_size: 0
    .sgpr_count:     108
    .sgpr_spill_count: 244
    .symbol:         _Z10fwd_kernel4Args.kd
    .uniform_work_group_size: 1
    .uses_dynamic_stack: false
    .vgpr_count:     256
    .vgpr_spill_count: 0
    .wavefront_size: 64
